# v16 + LayerNorm loop (2nd instance): next row's loads issued behind the previous row's last stores (a full row of latency cover)
# baseline (speedup 1.0000x reference)
; DI unsigned pk2(float lo, float hi) { f32x2 v = {lo, hi}; bf16x2_t b = __builtin_convertvector(v, bf16x2_t); return __builtin_bit_cast(unsigned, b); }
; DI float hlo(unsigned u) { return (float)__builtin_bit_cast(f16x2_t, u).x; }
; DI float hhi(unsigned u) { return (float)__builtin_bit_cast(f16x2_t, u).y; }
; DI void lnmod_phase(const Args& A, LAS unsigned char* lds, int tid, int bid, int G, bool init, int l_norm, int i_norm, int l_mod, int i_mod, bool want_dt, int nrows, bool ctx_partial, const float* gprev, const float* bprev) {
;     ...
;     u32x2 un[4]; f32x4 fn[4];
;     int mi_cur = -1; f32x4 shv[4], sclv[4];
;     { const int row = bid * 8 + wave;
;       if (row < nrows) {
;           if (init) { const float* xin = row < M_LAT ? A.in[I_X] + (size_t)row * DM : A.in[I_CTX] + (size_t)(row - M_LAT) * DM;
; #pragma unroll
;               for (int j = 0; j < 4; ++j) fn[j] = *(const f32x4*)(xin + 256 * j + 4 * lane); }
;           else {
; #pragma unroll
;               for (int j = 0; j < 4; ++j) un[j] = *(const u32x2*)(X16 + (size_t)row * DM + 256 * j + 4 * lane); } } }
;     for (int row = bid * 8 + wave; row < nrows; row += G * 8) {
;         bf16* xout = X16 + (size_t)row * DM;
;         f32x4 v[4];
; #pragma unroll
;         for (int j = 0; j < 4; ++j) v[j] = init ? fn[j] : (f32x4){hlo(un[j].x), hhi(un[j].x), hlo(un[j].y), hhi(un[j].y)};
;         { const int rown = row + G * 8;
;           if (rown < nrows) {
;               if (init) { const float* xin = rown < M_LAT ? A.in[I_X] + (size_t)rown * DM : A.in[I_CTX] + (size_t)(rown - M_LAT) * DM;
; #pragma unroll
;                   for (int j = 0; j < 4; ++j) fn[j] = *(const f32x4*)(xin + 256 * j + 4 * lane); }
;               else {
; #pragma unroll
;                   for (int j = 0; j < 4; ++j) un[j] = *(const u32x2*)(X16 + (size_t)rown * DM + 256 * j + 4 * lane); } } }
;     ...
;             for (int j = 0; j < 4; ++j) {
;                 const f32x4 a = v[j] * sclv[j] + shv[j];
;                 u32x2 w; w.x = pk2(a.x, a.y); w.y = pk2(a.z, a.w);
;                 *(u32x2*)(Abuf + (size_t)row * DM + 256 * j + 4 * lane) = w;
.LBB0_225:
	v_ashrrev_i32_e32 v116, 6, v152
	v_readlane_b32 s1, v253, 33
	v_readlane_b32 s4, v253, 35
	s_add_i32 s6, s4, 1
	s_waitcnt vmcnt(0)
	v_lshl_add_u32 v80, s1, 3, v116
	v_readlane_b32 s1, v253, 39
	v_readlane_b32 s5, v253, 36
	s_nop 0
	v_cmp_gt_i32_e32 vcc, s1, v80
	s_and_saveexec_b64 s[8:9], vcc
	s_cbranch_execz .LBB0_242
	v_ashrrev_i32_e32 v81, 31, v80
	v_readlane_b32 s4, v251, 45
	v_lshlrev_b64 v[82:83], 11, v[80:81]
	v_readlane_b32 s5, v251, 46
	v_lshlrev_b32_e32 v146, 3, v85
	v_readlane_b32 s16, v252, 54
	v_lshl_add_u64 v[32:33], s[4:5], 0, v[82:83]
	v_lshl_add_u64 v[32:33], v[32:33], 0, v[146:147]
	global_load_dwordx2 v[66:67], v[32:33], off
	global_load_dwordx2 v[72:73], v[32:33], off offset:512
	global_load_dwordx2 v[70:71], v[32:33], off offset:1024
	global_load_dwordx2 v[76:77], v[32:33], off offset:1536
	v_readlane_b32 s4, v253, 37
	v_readlane_b32 s5, v253, 38
	s_and_b64 s[4:5], s[4:5], exec
	s_cselect_b32 s7, s6, -1
	s_addk_i32 s0, 0x400
	s_ashr_i32 s1, s0, 31
	s_lshl_b64 s[0:1], s[0:1], 2
	v_readlane_b32 s28, v253, 2
	v_readlane_b32 s29, v253, 3
	s_add_u32 s4, s28, s0
	v_readlane_b32 s30, v253, 4
	s_addc_u32 s5, s29, s1
	v_readlane_b32 s31, v253, 5
	s_add_u32 s0, s30, s0
	v_readlane_b32 s14, v253, 34
	s_addc_u32 s1, s31, s1
	s_lshl_b32 s14, s14, 3
	v_readlane_b32 s17, v252, 55
	s_cmp_gt_i32 s7, -1
	v_readlane_b32 s18, v252, 56
	v_readlane_b32 s19, v252, 57
	v_lshlrev_b32_e32 v32, 4, v85
	v_mov_b32_e32 v33, v147
	s_cselect_b64 s[16:17], -1, 0
	v_cmp_eq_u32_e32 vcc, 0, v85
	v_lshl_add_u64 v[86:87], s[4:5], 0, v[32:33]
	v_lshl_add_u64 v[88:89], s[0:1], 0, v[32:33]
	s_and_b64 s[18:19], s[16:17], vcc
	v_add_u32_e32 v32, s14, v80
	s_cmp_lt_i32 s7, 0
	v_ashrrev_i32_e32 v33, 31, v32
	v_readlane_b32 s20, v252, 58
	v_readlane_b32 s21, v252, 59
	s_cselect_b64 s[0:1], -1, 0
	v_lshlrev_b64 v[90:91], 11, v[32:33]
	v_mov_b64_e32 v[32:33], 0x240000
	s_and_b64 s[20:21], s[2:3], s[0:1]
	v_lshl_add_u64 v[92:93], v[80:81], 3, v[32:33]
	v_lshlrev_b64 v[32:33], 12, v[80:81]
	v_readlane_b32 s0, v252, 27
	v_readlane_b32 s22, v252, 60
	v_readlane_b32 s23, v252, 61
	v_readlane_b32 s24, v252, 62
	v_readlane_b32 s25, v252, 63
	v_readlane_b32 s26, v253, 0
	v_readlane_b32 s27, v253, 1
	s_ashr_i32 s15, s14, 31
	v_lshl_or_b32 v32, v85, 4, v32
	v_readlane_b32 s1, v252, 28
	v_lshlrev_b32_e32 v84, 2, v85
	s_mul_hi_u32 s23, s7, 9
	s_mul_i32 s22, s7, 9
	v_or_b32_e32 v90, v90, v146
	s_lshl_b64 s[24:25], s[14:15], 11
	s_lshl_b64 s[26:27], s[14:15], 3
	v_or_b32_e32 v82, v82, v146
	v_lshl_add_u64 v[94:95], s[0:1], 0, v[32:33]
	s_lshl_b64 s[28:29], s[14:15], 12
	v_mov_b32_e32 v117, -1
	s_mov_b64 s[30:31], 0
	v_mov_b32_e32 v118, v80
	s_waitcnt vmcnt(0)
	s_mov_b32 s76, 1
	s_branch .LBB0_229
.LBB0_227:
	s_or_b64 exec, exec, s[0:1]
	s_waitcnt vmcnt(3)
	v_pk_fma_f32 v[66:67], v[66:67], v[58:59], v[46:47]
	v_pk_fma_f32 v[64:65], v[64:65], v[56:57], v[44:45]
	s_mov_b32 s0, 0x3800000
	v_cvt_pk_bf16_f32 v64, v64, v65
	v_cvt_pk_bf16_f32 v65, v66, v67
	v_add_co_u32_e32 v66, vcc, s0, v104
	s_waitcnt vmcnt(2)
	v_pk_fma_f32 v[68:69], v[68:69], v[48:49], v[40:41]
	v_addc_co_u32_e32 v67, vcc, 0, v105, vcc
	global_store_dwordx2 v[66:67], v[64:65], off
	v_pk_fma_f32 v[64:65], v[70:71], v[50:51], v[42:43]
	v_cvt_pk_bf16_f32 v68, v68, v69
	v_cvt_pk_bf16_f32 v69, v64, v65
	global_store_dwordx2 v[66:67], v[68:69], off offset:512
	s_waitcnt vmcnt(3)
	v_pk_fma_f32 v[64:65], v[74:75], v[54:55], v[38:39]
	v_pk_fma_f32 v[68:69], v[72:73], v[52:53], v[36:37]
	s_nop 0
	v_cvt_pk_bf16_f32 v68, v68, v69
	v_cvt_pk_bf16_f32 v69, v64, v65
	global_store_dwordx2 v[66:67], v[68:69], off offset:1024
	s_waitcnt vmcnt(3)
	v_pk_fma_f32 v[64:65], v[78:79], v[62:63], v[34:35]
	v_pk_fma_f32 v[68:69], v[76:77], v[60:61], v[32:33]
	s_nop 0
	v_cvt_pk_bf16_f32 v68, v68, v69
	v_cvt_pk_bf16_f32 v69, v64, v65
	global_store_dwordx2 v[66:67], v[68:69], off offset:1536
	v_add_u32_e32 v140, s14, v81
	v_readlane_b32 s78, v253, 39
	v_readlane_b32 s80, v253, 25
	v_readlane_b32 s81, v253, 26
	s_nop 1
	v_cmp_gt_i32_e32 vcc, s78, v140
	s_and_saveexec_b64 s[82:83], vcc
	s_cbranch_execz .Llnp2_pfa
	v_lshl_add_u64 v[138:139], s[80:81], 0, v[90:91]
	v_lshl_add_u64 v[138:139], v[138:139], 0, s[24:25]
	v_add_co_u32_e32 v138, vcc, 0x21200000, v138
	s_nop 1
	v_addc_co_u32_e32 v139, vcc, 0, v139, vcc
	global_load_dwordx2 v[96:97], v[138:139], off
	global_load_dwordx2 v[98:99], v[138:139], off offset:512
	global_load_dwordx2 v[100:101], v[138:139], off offset:1024
	global_load_dwordx2 v[102:103], v[138:139], off offset:1536
.Llnp2_pfa:
	s_or_b64 exec, exec, s[82:83]

; DI void lnmod_phase(const Args& A, LAS unsigned char* lds, int tid, int bid, int G, bool init, int l_norm, int i_norm, int l_mod, int i_mod, bool want_dt, int nrows, bool ctx_partial, const float* gprev, const float* bprev) {
;     ...
;         { const int rown = row + G * 8;
;           if (rown < nrows) {
;               if (init) { const float* xin = rown < M_LAT ? A.in[I_X] + (size_t)rown * DM : A.in[I_CTX] + (size_t)(rown - M_LAT) * DM;
; #pragma unroll
;                   for (int j = 0; j < 4; ++j) fn[j] = *(const f32x4*)(xin + 256 * j + 4 * lane); }
;               else {
; #pragma unroll
;                   for (int j = 0; j < 4; ++j) un[j] = *(const u32x2*)(X16 + (size_t)rown * DM + 256 * j + 4 * lane); } } }
.LBB0_229:
	v_add_u32_e32 v81, s14, v118
	v_readlane_b32 s0, v253, 39
	s_nop 1
	v_cmp_gt_i32_e32 vcc, s0, v81
	v_cmp_le_i32_e64 s[0:1], s0, v81
	s_cmp_eq_u32 s76, 0
	s_cbranch_scc1 .Llnp2_skip0
	s_and_saveexec_b64 s[4:5], vcc
	s_cbranch_execz .LBB0_231
	v_readlane_b32 s36, v253, 23
	v_readlane_b32 s38, v253, 25
	v_readlane_b32 s39, v253, 26
	v_readlane_b32 s37, v253, 24
	s_nop 0
	v_lshl_add_u64 v[64:65], s[38:39], 0, v[90:91]
	v_add_co_u32_e32 v64, vcc, 0x21200000, v64
	s_nop 1
	v_addc_co_u32_e32 v65, vcc, 0, v65, vcc
	global_load_dwordx2 v[96:97], v[64:65], off
	global_load_dwordx2 v[98:99], v[64:65], off offset:512
	global_load_dwordx2 v[100:101], v[64:65], off offset:1024
	global_load_dwordx2 v[102:103], v[64:65], off offset:1536

; DI unsigned pkh2(float lo, float hi) { return __builtin_bit_cast(unsigned, __builtin_amdgcn_cvt_pkrtz(lo, hi)); }
; DI float hlo(unsigned u) { return (float)__builtin_bit_cast(f16x2_t, u).x; }
; DI float hhi(unsigned u) { return (float)__builtin_bit_cast(f16x2_t, u).y; }
; DI void lnmod_phase(const Args& A, LAS unsigned char* lds, int tid, int bid, int G, bool init, int l_norm, int i_norm, int l_mod, int i_mod, bool want_dt, int nrows, bool ctx_partial, const float* gprev, const float* bprev) {
;     ...
;         for (int j = 0; j < 4; ++j) v[j] = init ? fn[j] : (f32x4){hlo(un[j].x), hhi(un[j].x), hlo(un[j].y), hhi(un[j].y)};
;         { const int rown = row + G * 8;
;           if (rown < nrows) {
;               if (init) { const float* xin = rown < M_LAT ? A.in[I_X] + (size_t)rown * DM : A.in[I_CTX] + (size_t)(rown - M_LAT) * DM;
; #pragma unroll
;                   for (int j = 0; j < 4; ++j) fn[j] = *(const f32x4*)(xin + 256 * j + 4 * lane); }
;               else {
; #pragma unroll
;                   for (int j = 0; j < 4; ++j) un[j] = *(const u32x2*)(X16 + (size_t)rown * DM + 256 * j + 4 * lane); } } }
;         f32x2* STAT = (f32x2*)(A.ws + WS_STAT);
;         if (ctx_partial && row >= M_LAT) {
;             { const f32x2 st = STAT[row];
; #pragma unroll
;               for (int j = 0; j < 4; ++j) v[j] = (v[j] - st.x) * st.y * *(const f32x4*)(gprev + 256 * j + 4 * lane) + *(const f32x4*)(bprev + 256 * j + 4 * lane); }
;             const float* t0 = (const float*)(A.ws + WS_T) + (size_t)(row - M_LAT) * DM; const float* t1 = t0 + (size_t)M_CTX * DM; const float* t2 = t1 + (size_t)M_CTX * DM; const float* t3 = t2 + (size_t)M_CTX * DM;
; #pragma unroll
;             for (int j = 0; j < 4; ++j) { v[j] = v[j] * ALPHA + (*(const f32x4*)(t0 + 256 * j + 4 * lane) + *(const f32x4*)(t1 + 256 * j + 4 * lane)) + (*(const f32x4*)(t2 + 256 * j + 4 * lane) + *(const f32x4*)(t3 + 256 * j + 4 * lane)); u32x2 w_; w_.x = pkh2(v[j].x, v[j].y); w_.y = pkh2(v[j].z, v[j].w); *(u32x2*)(xout + 256 * j + 4 * lane) = w_; }
.Llnp2_skip0:
	s_mov_b32 s76, 0
	v_cvt_f32_f16_sdwa v108, v66 dst_sel:DWORD dst_unused:UNUSED_PAD src0_sel:WORD_1
	v_cvt_f32_f16_e32 v64, v66
	v_cvt_f32_f16_sdwa v65, v67 dst_sel:DWORD dst_unused:UNUSED_PAD src0_sel:WORD_1
	v_cvt_f32_f16_e32 v109, v67
	v_cvt_f32_f16_sdwa v66, v72 dst_sel:DWORD dst_unused:UNUSED_PAD src0_sel:WORD_1
	v_cvt_f32_f16_e32 v68, v72
	v_cvt_f32_f16_sdwa v69, v73 dst_sel:DWORD dst_unused:UNUSED_PAD src0_sel:WORD_1
	v_cvt_f32_f16_e32 v67, v73
	v_cvt_f32_f16_sdwa v73, v70 dst_sel:DWORD dst_unused:UNUSED_PAD src0_sel:WORD_1
	v_cvt_f32_f16_e32 v72, v70
	v_cvt_f32_f16_sdwa v75, v71 dst_sel:DWORD dst_unused:UNUSED_PAD src0_sel:WORD_1
	v_cvt_f32_f16_e32 v74, v71
	v_cvt_f32_f16_sdwa v70, v76 dst_sel:DWORD dst_unused:UNUSED_PAD src0_sel:WORD_1
	v_cvt_f32_f16_e32 v76, v76
	v_cvt_f32_f16_sdwa v106, v77 dst_sel:DWORD dst_unused:UNUSED_PAD src0_sel:WORD_1
	v_cvt_f32_f16_e32 v78, v77
	s_movk_i32 s4, 0x7fff
	v_cmp_lt_i32_e32 vcc, s4, v118
	v_readlane_b32 s4, v253, 37
	v_readlane_b32 s40, v253, 23
	v_readlane_b32 s5, v253, 38
	v_readlane_b32 s42, v253, 25
	v_readlane_b32 s43, v253, 26
	s_and_b64 s[36:37], s[4:5], vcc
	v_readlane_b32 s41, v253, 24
	v_lshl_add_u64 v[104:105], s[42:43], 0, v[82:83]
	s_and_saveexec_b64 s[4:5], s[36:37]
	s_cbranch_execz .LBB0_233
	v_readlane_b32 s38, v253, 25
	v_readlane_b32 s39, v253, 26
	v_add_u32_e32 v146, 0xffff8000, v118
	s_nop 1
	v_lshl_add_u64 v[110:111], s[38:39], 0, v[92:93]
	global_load_dwordx2 v[120:121], v[110:111], off
	v_readlane_b32 s36, v251, 61
	v_readlane_b32 s37, v251, 62
	s_mov_b32 s7, 0x800000
	global_load_dwordx4 v[130:133], v[86:87], off
	global_load_dwordx4 v[112:115], v[88:89], off
	global_load_dwordx4 v[134:137], v[86:87], off offset:1024
	global_load_dwordx4 v[138:141], v[88:89], off offset:1024
	global_load_dwordx4 v[154:157], v[86:87], off offset:2048
	global_load_dwordx4 v[160:163], v[88:89], off offset:2048
	global_load_dwordx4 v[164:167], v[86:87], off offset:3072
	global_load_dwordx4 v[168:171], v[88:89], off offset:3072
	s_waitcnt vmcnt(8)
	v_sub_f32_e32 v111, v108, v120
	v_sub_f32_e32 v110, v64, v120
	v_sub_f32_e32 v64, v109, v120
	v_pk_mul_f32 v[122:123], v[120:121], v[110:111] op_sel:[1,0]
	v_sub_f32_e32 v65, v65, v120
	v_pk_mul_f32 v[64:65], v[120:121], v[64:65] op_sel:[1,0]
	v_sub_f32_e32 v69, v69, v120
	s_waitcnt vmcnt(6)
	v_pk_fma_f32 v[114:115], v[132:133], v[64:65], v[114:115]
	v_sub_f32_e32 v65, v66, v120
	v_sub_f32_e32 v64, v68, v120
	v_sub_f32_e32 v68, v67, v120
	v_pk_fma_f32 v[128:129], v[130:131], v[122:123], v[112:113]
	v_pk_mul_f32 v[112:113], v[120:121], v[68:69] op_sel:[1,0]
	v_pk_mul_f32 v[68:69], v[120:121], v[64:65] op_sel:[1,0]
	s_waitcnt vmcnt(4)
	v_pk_fma_f32 v[68:69], v[68:69], v[134:135], v[138:139]
	v_pk_fma_f32 v[138:139], v[112:113], v[136:137], v[140:141]
	v_sub_f32_e32 v135, v73, v120
	v_sub_f32_e32 v134, v72, v120
	v_sub_f32_e32 v137, v75, v120
	v_sub_f32_e32 v136, v74, v120
	v_pk_mul_f32 v[140:141], v[120:121], v[136:137] op_sel:[1,0]
	v_pk_mul_f32 v[112:113], v[120:121], v[134:135] op_sel:[1,0]
	s_waitcnt vmcnt(2)
	v_pk_fma_f32 v[160:161], v[112:113], v[154:155], v[160:161]
	v_pk_fma_f32 v[162:163], v[140:141], v[156:157], v[162:163]
	v_sub_f32_e32 v154, v76, v120
	v_sub_f32_e32 v156, v78, v120
	v_sub_f32_e32 v155, v70, v120
	v_sub_f32_e32 v157, v106, v120
	v_pk_mul_f32 v[154:155], v[120:121], v[154:155] op_sel:[1,0]
	v_pk_mul_f32 v[70:71], v[120:121], v[156:157] op_sel:[1,0]
	s_waitcnt vmcnt(0)
	v_pk_fma_f32 v[156:157], v[154:155], v[164:165], v[168:169]
	v_lshlrev_b64 v[64:65], 12, v[146:147]
	v_lshl_add_u64 v[64:65], s[36:37], 0, v[64:65]
	v_lshlrev_b32_e32 v146, 2, v84
	v_lshl_add_u64 v[110:111], v[64:65], 0, v[146:147]
	v_add_co_u32_e32 v130, vcc, s7, v110
	global_load_dwordx4 v[120:123], v[110:111], off
	s_nop 1
	v_addc_co_u32_e32 v131, vcc, 0, v111, vcc
	global_load_dwordx4 v[124:127], v[130:131], off
	s_mov_b64 s[36:37], 0x800000
	v_lshl_add_u64 v[132:133], v[110:111], 0, s[36:37]
	s_mov_b64 s[36:37], 0x1000000
	v_lshl_add_u64 v[76:77], v[110:111], 0, s[36:37]
	s_mov_b64 s[36:37], 0x1800000
	v_lshl_add_u64 v[134:135], v[110:111], 0, s[36:37]
	s_mov_b32 s7, 0x1000000
	v_add_co_u32_e32 v136, vcc, s7, v110
	s_mov_b32 s7, 0x1800000
	s_nop 1
	v_addc_co_u32_e32 v137, vcc, 0, v111, vcc
	global_load_dwordx4 v[172:175], v[136:137], off
	v_add_co_u32_e32 v142, vcc, s7, v110
	s_nop 1
	v_addc_co_u32_e32 v143, vcc, 0, v111, vcc
	global_load_dwordx4 v[176:179], v[142:143], off
	global_load_dwordx4 v[180:183], v[110:111], off offset:1024
	global_load_dwordx4 v[184:187], v[132:133], off offset:1024
	global_load_dwordx4 v[188:191], v[76:77], off offset:1024
	global_load_dwordx4 v[192:195], v[134:135], off offset:1024
	global_load_dwordx4 v[196:199], v[110:111], off offset:2048
	global_load_dwordx4 v[200:203], v[132:133], off offset:2048
	global_load_dwordx4 v[204:207], v[76:77], off offset:2048
	global_load_dwordx4 v[218:221], v[134:135], off offset:2048
	global_load_dwordx4 v[222:225], v[110:111], off offset:3072
	global_load_dwordx4 v[226:229], v[132:133], off offset:3072
	global_load_dwordx4 v[230:233], v[76:77], off offset:3072
	global_load_dwordx4 v[234:237], v[134:135], off offset:3072
	s_nop 0
	v_pk_fma_f32 v[70:71], v[70:71], v[166:167], v[170:171]
	s_mov_b32 s36, 0x3fd744fd
	s_waitcnt vmcnt(14)
	v_pk_add_f32 v[130:131], v[122:123], v[126:127]
	v_pk_add_f32 v[106:107], v[120:121], v[124:125]
	v_pk_fma_f32 v[130:131], v[114:115], s[36:37], v[130:131] op_sel_hi:[1,0,1]
	v_pk_fma_f32 v[114:115], v[128:129], s[36:37], v[106:107] op_sel_hi:[1,0,1]
	s_nop 0
	s_mov_b32 s7, 0x21200000
	s_nop 0
	s_waitcnt vmcnt(12)
; DI unsigned pkh2(float lo, float hi) { return __builtin_bit_cast(unsigned, __builtin_amdgcn_cvt_pkrtz(lo, hi)); }
; DI void lnmod_phase(const Args& A, LAS unsigned char* lds, int tid, int bid, int G, bool init, int l_norm, int i_norm, int l_mod, int i_mod, bool want_dt, int nrows, bool ctx_partial, const float* gprev, const float* bprev) {
;     ...
;             const float* t0 = (const float*)(A.ws + WS_T) + (size_t)(row - M_LAT) * DM; const float* t1 = t0 + (size_t)M_CTX * DM; const float* t2 = t1 + (size_t)M_CTX * DM; const float* t3 = t2 + (size_t)M_CTX * DM;
; #pragma unroll
;             for (int j = 0; j < 4; ++j) { v[j] = v[j] * ALPHA + (*(const f32x4*)(t0 + 256 * j + 4 * lane) + *(const f32x4*)(t1 + 256 * j + 4 * lane)) + (*(const f32x4*)(t2 + 256 * j + 4 * lane) + *(const f32x4*)(t3 + 256 * j + 4 * lane)); u32x2 w_; w_.x = pkh2(v[j].x, v[j].y); w_.y = pkh2(v[j].z, v[j].w); *(u32x2*)(xout + 256 * j + 4 * lane) = w_; }
	v_pk_add_f32 v[142:143], v[174:175], v[178:179]
	v_pk_add_f32 v[172:173], v[172:173], v[176:177]
	v_pk_add_f32 v[142:143], v[130:131], v[142:143]
	v_pk_add_f32 v[130:131], v[114:115], v[172:173]
	v_add_co_u32_e32 v114, vcc, s7, v104
	v_cvt_pkrtz_f16_f32 v172, v130, v131
	v_cvt_pkrtz_f16_f32 v173, v142, v143
	v_addc_co_u32_e32 v115, vcc, 0, v105, vcc
	global_store_dwordx2 v[114:115], v[172:173], off
	s_nop 0
	s_waitcnt vmcnt(10)
	v_pk_add_f32 v[182:183], v[182:183], v[186:187]
	v_pk_add_f32 v[180:181], v[180:181], v[184:185]
	v_pk_fma_f32 v[138:139], v[138:139], s[36:37], v[182:183] op_sel_hi:[1,0,1]
	v_pk_fma_f32 v[68:69], v[68:69], s[36:37], v[180:181] op_sel_hi:[1,0,1]
	s_waitcnt vmcnt(8)
	v_pk_add_f32 v[190:191], v[190:191], v[194:195]
	v_pk_add_f32 v[188:189], v[188:189], v[192:193]
	v_pk_add_f32 v[128:129], v[138:139], v[190:191]
	v_pk_add_f32 v[68:69], v[68:69], v[188:189]
	v_cvt_pkrtz_f16_f32 v139, v128, v129
	v_cvt_pkrtz_f16_f32 v138, v68, v69
	global_store_dwordx2 v[114:115], v[138:139], off offset:512
	s_waitcnt vmcnt(6)
	v_pk_add_f32 v[138:139], v[198:199], v[202:203]
	v_pk_add_f32 v[196:197], v[196:197], v[200:201]
	v_pk_fma_f32 v[138:139], v[162:163], s[36:37], v[138:139] op_sel_hi:[1,0,1]
	v_pk_fma_f32 v[200:201], v[160:161], s[36:37], v[196:197] op_sel_hi:[1,0,1]
	s_waitcnt vmcnt(4)
	v_pk_add_f32 v[206:207], v[206:207], v[220:221]
	v_pk_add_f32 v[204:205], v[204:205], v[218:219]
	v_pk_add_f32 v[206:207], v[138:139], v[206:207]
	v_pk_add_f32 v[204:205], v[200:201], v[204:205]
	v_cvt_pkrtz_f16_f32 v139, v206, v207
	v_cvt_pkrtz_f16_f32 v138, v204, v205
	global_store_dwordx2 v[114:115], v[138:139], off offset:1024
	s_nop 0
	s_waitcnt vmcnt(2)
	v_pk_add_f32 v[224:225], v[224:225], v[228:229]
	v_pk_add_f32 v[222:223], v[222:223], v[226:227]
	v_pk_fma_f32 v[70:71], v[70:71], s[36:37], v[224:225] op_sel_hi:[1,0,1]
	v_pk_fma_f32 v[156:157], v[156:157], s[36:37], v[222:223] op_sel_hi:[1,0,1]
	s_nop 0
	s_waitcnt vmcnt(0)
	v_pk_add_f32 v[236:237], v[232:233], v[236:237]
	v_pk_add_f32 v[234:235], v[230:231], v[234:235]
	v_pk_add_f32 v[236:237], v[70:71], v[236:237]
	v_pk_add_f32 v[234:235], v[156:157], v[234:235]
	v_cvt_pkrtz_f16_f32 v157, v236, v237
	v_cvt_pkrtz_f16_f32 v156, v234, v235
	global_store_dwordx2 v[114:115], v[156:157], off offset:1536
	v_mov_b32_e32 v230, v131
	v_mov_b32_e32 v231, v142
	v_mov_b32_e32 v131, v143
	v_mov_b32_e32 v156, v69
	v_mov_b32_e32 v157, v128
	v_mov_b32_e32 v69, v129
	v_mov_b32_e32 v70, v235
	v_mov_b32_e32 v142, v237
	v_mov_b32_e32 v64, v130
	v_mov_b32_e32 v65, v131
	v_mov_b32_e32 v66, v156
	v_mov_b32_e32 v67, v157
	v_mov_b32_e32 v72, v204
	v_mov_b32_e32 v73, v205
	v_mov_b32_e32 v74, v206
	v_mov_b32_e32 v75, v207
	v_mov_b32_e32 v76, v234
	v_mov_b32_e32 v78, v236
	v_mov_b32_e32 v106, v142
	v_mov_b32_e32 v108, v230
	v_mov_b32_e32 v109, v231
; DI void lnmod_phase(const Args& A, LAS unsigned char* lds, int tid, int bid, int G, bool init, int l_norm, int i_norm, int l_mod, int i_mod, bool want_dt, int nrows, bool ctx_partial, const float* gprev, const float* bprev) {
;     ...
;         if (l_norm >= 0) {
;             float s = 0.f, s2 = 0.f;
; #pragma unroll
;             for (int j = 0; j < 4; ++j) { s += (v[j].x + v[j].y) + (v[j].z + v[j].w); s2 += (v[j].x * v[j].x + v[j].y * v[j].y) + (v[j].z * v[j].z + v[j].w * v[j].w); }
;             wave_sum2(s, s2);
;             const float mean = s * (1.f / DM);
;             const float rstd = 1.0f / sqrtf(fmaxf(s2 * (1.f / DM) - mean * mean, 0.f) + 1e-5f);
; #pragma unroll
;             for (int j = 0; j < 4; ++j) v[j] = v[j] - mean;
;             if (l_mod >= 0 && lane == 0) STAT[row] = (f32x2){mean, rstd};
.LBB0_233:
	s_or_b64 exec, exec, s[4:5]
	s_andn2_b64 vcc, exec, s[2:3]
	s_cbranch_vccnz .LBB0_237
	v_pk_add_f32 v[110:111], v[108:109], v[64:65]
	v_mul_f32_e32 v77, v65, v65
	v_add_f32_e32 v71, v110, v111
	v_add_f32_e32 v107, 0, v71
	v_mul_f32_e32 v71, v108, v108
	v_fmac_f32_e32 v71, v64, v64
	v_fmac_f32_e32 v77, v109, v109
	v_pk_add_f32 v[110:111], v[66:67], v[68:69]
	v_add_f32_e32 v71, v71, v77
	v_pk_add_f32 v[110:111], v[110:111], v[110:111] op_sel_hi:[0,1]
	v_mul_f32_e32 v77, v66, v66
	v_mul_f32_e32 v79, v69, v69
	v_fmac_f32_e32 v77, v68, v68
	v_fmac_f32_e32 v79, v67, v67
	v_mul_f32_e32 v110, v73, v73
	v_mul_f32_e32 v112, v75, v75
	v_add_f32_e32 v77, v77, v79
	v_fmac_f32_e32 v110, v72, v72
	v_fmac_f32_e32 v112, v74, v74
	v_add_f32_e32 v79, v71, v77
	v_add_f32_e32 v110, v110, v112
	v_add_f32_e32 v77, v72, v73
	v_add_f32_e32 v71, v74, v75
	v_add_f32_e32 v114, v110, v79
	v_mov_b32_e32 v79, v111
	v_pk_add_f32 v[112:113], v[76:77], v[70:71]
	v_pk_add_f32 v[110:111], v[78:79], v[106:107]
	v_mul_f32_e32 v77, v70, v70
	v_mul_f32_e32 v79, v106, v106
	v_fmac_f32_e32 v77, v76, v76
	v_fmac_f32_e32 v79, v78, v78
	v_add_f32_e32 v77, v77, v79
	v_and_b32_e32 v79, 64, v210
	v_add_u32_e32 v79, 64, v79
	v_xor_b32_e32 v107, 1, v210
	v_cmp_lt_i32_e32 vcc, v107, v79
	v_pk_add_f32 v[110:111], v[112:113], v[110:111]
	v_add_f32_e32 v77, v77, v114
	v_cndmask_b32_e32 v107, v210, v107, vcc
	v_add_f32_e32 v71, v110, v111
	v_lshlrev_b32_e32 v107, 2, v107
	s_nop 1
	v_mov_b32_dpp v110, v71 quad_perm:[1,0,3,2] row_mask:0xf bank_mask:0xf
	v_mov_b32_dpp v107, v77 quad_perm:[1,0,3,2] row_mask:0xf bank_mask:0xf
	s_mov_b32 s4, 0x3a800000
	s_waitcnt lgkmcnt(1)
	v_add_f32_e32 v71, v71, v110
	s_waitcnt lgkmcnt(0)
	v_add_f32_e32 v77, v77, v107
	v_xor_b32_e32 v107, 2, v210
	v_cmp_lt_i32_e32 vcc, v107, v79
	s_nop 1
	v_cndmask_b32_e32 v107, v210, v107, vcc
	v_lshlrev_b32_e32 v107, 2, v107
	s_nop 1
	v_mov_b32_dpp v110, v71 quad_perm:[2,3,0,1] row_mask:0xf bank_mask:0xf
	v_mov_b32_dpp v107, v77 quad_perm:[2,3,0,1] row_mask:0xf bank_mask:0xf
	s_waitcnt lgkmcnt(1)
	v_add_f32_e32 v71, v71, v110
	s_waitcnt lgkmcnt(0)
	v_add_f32_e32 v77, v77, v107
	v_xor_b32_e32 v107, 4, v210
	v_cmp_lt_i32_e32 vcc, v107, v79
	s_nop 1
	v_cndmask_b32_e32 v107, v210, v107, vcc
	v_lshlrev_b32_e32 v107, 2, v107
	s_nop 1
	v_mov_b32_dpp v110, v71 row_half_mirror row_mask:0xf bank_mask:0xf
	v_mov_b32_dpp v107, v77 row_half_mirror row_mask:0xf bank_mask:0xf
	s_waitcnt lgkmcnt(1)
	v_add_f32_e32 v71, v71, v110
	s_waitcnt lgkmcnt(0)
	v_add_f32_e32 v77, v77, v107
	v_xor_b32_e32 v107, 8, v210
	v_cmp_lt_i32_e32 vcc, v107, v79
	s_nop 1
	v_cndmask_b32_e32 v107, v210, v107, vcc
	v_lshlrev_b32_e32 v107, 2, v107
	s_nop 1
	v_mov_b32_dpp v110, v71 row_mirror row_mask:0xf bank_mask:0xf
	v_mov_b32_dpp v107, v77 row_mirror row_mask:0xf bank_mask:0xf
	s_waitcnt lgkmcnt(1)
	v_add_f32_e32 v71, v71, v110
	s_waitcnt lgkmcnt(0)
	v_add_f32_e32 v77, v77, v107
	v_xor_b32_e32 v107, 16, v210
	v_cmp_lt_i32_e32 vcc, v107, v79
	s_nop 1
	v_cndmask_b32_e32 v107, v210, v107, vcc
	v_lshlrev_b32_e32 v107, 2, v107
	v_mov_b32_e32 v110, v71
	v_mov_b32_e32 v107, v77
	s_nop 1
	v_permlane16_swap_b32_e32 v71, v110
	v_permlane16_swap_b32_e32 v77, v107
	s_waitcnt lgkmcnt(1)
	v_add_f32_e32 v71, v71, v110
	s_waitcnt lgkmcnt(0)
	v_add_f32_e32 v77, v77, v107
	v_xor_b32_e32 v107, 32, v210
	v_cmp_lt_i32_e32 vcc, v107, v79
	s_nop 1
	v_cndmask_b32_e32 v79, v210, v107, vcc
	v_lshlrev_b32_e32 v79, 2, v79
	v_mov_b32_e32 v107, v71
	v_mov_b32_e32 v79, v77
	s_nop 1
	v_permlane32_swap_b32_e32 v71, v107
	v_permlane32_swap_b32_e32 v77, v79
	s_waitcnt lgkmcnt(1)
	v_add_f32_e32 v71, v71, v107
	v_mul_f32_e32 v112, 0x3a800000, v71
	s_waitcnt lgkmcnt(0)
	v_add_f32_e32 v77, v77, v79
	v_mul_f32_e32 v71, v112, v112
	v_fma_f32 v71, v77, s4, -v71
	v_max_f32_e32 v71, 0, v71
	v_add_f32_e32 v71, 0x3727c5ac, v71
	v_mul_f32_e32 v77, 0x4f800000, v71
	v_cmp_gt_f32_e32 vcc, s65, v71
	s_nop 1
	v_cndmask_b32_e32 v71, v71, v77, vcc
	v_sqrt_f32_e32 v77, v71
	s_nop 0
	v_add_u32_e32 v79, -1, v77
	v_fma_f32 v107, -v79, v77, v71
	v_cmp_ge_f32_e64 s[4:5], 0, v107
	v_add_u32_e32 v107, 1, v77
	s_nop 0
	v_cndmask_b32_e64 v79, v77, v79, s[4:5]
	v_fma_f32 v77, -v107, v77, v71
	v_cmp_lt_f32_e64 s[4:5], 0, v77
	s_nop 1
	v_cndmask_b32_e64 v77, v79, v107, s[4:5]
	v_mul_f32_e32 v79, 0x37800000, v77
	v_cndmask_b32_e32 v77, v77, v79, vcc
	v_cmp_class_f32_e32 vcc, v71, v208
	s_nop 1
	v_cndmask_b32_e32 v71, v77, v71, vcc
	v_div_scale_f32 v77, s[4:5], v71, v71, 1.0
	v_rcp_f32_e32 v79, v77
	s_nop 0
	v_fma_f32 v107, -v77, v79, 1.0
	v_fmac_f32_e32 v79, v107, v79
	v_div_scale_f32 v107, vcc, 1.0, v71, 1.0
	v_mul_f32_e32 v110, v107, v79
	v_fma_f32 v111, -v77, v110, v107
	v_fmac_f32_e32 v110, v111, v79
	v_fma_f32 v77, -v77, v110, v107
	v_div_fmas_f32 v77, v77, v79, v110
	v_div_fixup_f32 v110, v77, v71, 1.0
	s_waitcnt vmcnt(0)
	v_mov_b32_e32 v130, v96
	v_mov_b32_e32 v131, v97
	v_mov_b32_e32 v132, v98
	v_mov_b32_e32 v133, v99
	v_mov_b32_e32 v134, v100
	v_mov_b32_e32 v135, v101
	v_mov_b32_e32 v136, v102
	v_mov_b32_e32 v137, v103
	s_and_saveexec_b64 s[4:5], s[18:19]
	s_cbranch_execz .LBB0_236
	v_readlane_b32 s36, v253, 23
	v_readlane_b32 s38, v253, 25
	v_readlane_b32 s39, v253, 26
	v_mov_b32_e32 v113, v110
	v_readlane_b32 s37, v253, 24
	v_lshl_add_u64 v[114:115], s[38:39], 0, v[92:93]
	global_store_dwordx2 v[114:115], v[112:113], off

; DI void lnmod_phase(const Args& A, LAS unsigned char* lds, int tid, int bid, int G, bool init, int l_norm, int i_norm, int l_mod, int i_mod, bool want_dt, int nrows, bool ctx_partial, const float* gprev, const float* bprev) {
;     ...
;         if (l_norm >= 0) {
;             float s = 0.f, s2 = 0.f;
; #pragma unroll
;             for (int j = 0; j < 4; ++j) { s += (v[j].x + v[j].y) + (v[j].z + v[j].w); s2 += (v[j].x * v[j].x + v[j].y * v[j].y) + (v[j].z * v[j].z + v[j].w * v[j].w); }
;             wave_sum2(s, s2);
;             const float mean = s * (1.f / DM);
;             const float rstd = 1.0f / sqrtf(fmaxf(s2 * (1.f / DM) - mean * mean, 0.f) + 1e-5f);
; #pragma unroll
;             for (int j = 0; j < 4; ++j) v[j] = v[j] - mean;
;             if (l_mod >= 0 && lane == 0) STAT[row] = (f32x2){mean, rstd};
; #pragma unroll
;             for (int j = 0; j < 4; ++j) v[j] = v[j] * rstd * g[j] + bb[j];
;         }
;         if (init && lane == 0) STAT[row] = (f32x2){0.f, 1.f};
.LBB0_237:
	s_waitcnt vmcnt(0)
	v_mov_b32_e32 v130, v96
	v_mov_b32_e32 v131, v97
	v_mov_b32_e32 v132, v98
	v_mov_b32_e32 v133, v99
	v_mov_b32_e32 v134, v100
	v_mov_b32_e32 v135, v101
	v_mov_b32_e32 v136, v102
	v_mov_b32_e32 v137, v103
	v_mov_b32_e32 v79, v106
	v_mov_b32_e32 v77, v70
	v_mov_b32_e32 v71, v69
	v_mov_b32_e32 v70, v67
	v_mov_b32_e32 v69, v66
	v_mov_b32_e32 v67, v65
	v_mov_b32_e32 v66, v109
	v_mov_b32_e32 v65, v108
	s_and_b64 s[0:1], exec, s[0:1]
	s_or_b64 s[30:31], s[0:1], s[30:31]
	s_andn2_b64 vcc, exec, s[20:21]
	s_cbranch_vccnz .LBB0_239

; DI void lnmod_phase(const Args& A, LAS unsigned char* lds, int tid, int bid, int G, bool init, int l_norm, int i_norm, int l_mod, int i_mod, bool want_dt, int nrows, bool ctx_partial, const float* gprev, const float* bprev) {
;     ...
;         { const int rown = row + G * 8;
;           if (rown < nrows) {
;               if (init) { const float* xin = rown < M_LAT ? A.in[I_X] + (size_t)rown * DM : A.in[I_CTX] + (size_t)(rown - M_LAT) * DM;
; #pragma unroll
;                   for (int j = 0; j < 4; ++j) fn[j] = *(const f32x4*)(xin + 256 * j + 4 * lane); }
;               else {
; #pragma unroll
;                   for (int j = 0; j < 4; ++j) un[j] = *(const u32x2*)(X16 + (size_t)rown * DM + 256 * j + 4 * lane); } } }
.Llnp2_stub:
	v_add_u32_e32 v140, s14, v81
	v_readlane_b32 s78, v253, 39
	v_readlane_b32 s80, v253, 25
	v_readlane_b32 s81, v253, 26
	s_nop 1
	v_cmp_gt_i32_e32 vcc, s78, v140
	s_and_saveexec_b64 s[82:83], vcc
	s_cbranch_execz .Llnp2_pfb
	v_lshl_add_u64 v[138:139], s[80:81], 0, v[90:91]
	v_lshl_add_u64 v[138:139], v[138:139], 0, s[24:25]
	v_add_co_u32_e32 v138, vcc, 0x21200000, v138
	s_nop 1
	v_addc_co_u32_e32 v139, vcc, 0, v139, vcc
	global_load_dwordx2 v[96:97], v[138:139], off
	global_load_dwordx2 v[98:99], v[138:139], off offset:512
	global_load_dwordx2 v[100:101], v[138:139], off offset:1024
	global_load_dwordx2 v[102:103], v[138:139], off offset:1536
.Llnp2_pfb:
	s_or_b64 exec, exec, s[82:83]
	s_branch .LBB0_228
